# GEMM: first K-iteration peeled with srcC=0 MFMAs; the remaining per-tile accumulator zeroing (128 v_mov per wave) removed
# speedup vs baseline: 1.0130x; 1.0074x over previous
; #define PG8_STAGE(bufoff, gbase, voff) do { _Pragma("unroll") for (int _i = 0; _i < 2; ++_i) \
;         __builtin_amdgcn_global_load_lds((const unsigned*)((const char*)(gbase) + (voff)[_i]), (LAS unsigned*)(lds + (bufoff) + ldsw + _i * 8192), 16, 0, 0); } while (0)
; #define PG8_LDA(dst, b, h) do { _Pragma("unroll") for (int m = 0; m < 4; ++m) _Pragma("unroll") for (int k = 0; k < 2; ++k) dst[m][k] = *(const LAS bf16x8*)(lds + PG8_SA(b, h) + aoff + m * 2048 + k * 1024); } while (0)
; #define PG8_LDB(dst, b, h) do { _Pragma("unroll") for (int n = 0; n < 2; ++n) _Pragma("unroll") for (int k = 0; k < 2; ++k) dst[n][k] = *(const LAS bf16x8*)(lds + PG8_SB(b, h) + boff + n * 2048 + k * 1024); } while (0)
; #define PG8_MMA(ai, bj, At, Bt) do { __builtin_amdgcn_s_setprio(1); _Pragma("unroll") for (int m = 0; m < 4; ++m) _Pragma("unroll") for (int n = 0; n < 2; ++n) _Pragma("unroll") for (int k = 0; k < 2; ++k) \
;         acc[ai][bj][m][n] = __builtin_amdgcn_mfma_f32_16x16x32_bf16(Bt[n][k], At[m][k], acc[ai][bj][m][n], 0, 0, 0); __builtin_amdgcn_s_setprio(0); } while (0)
; #define PG8_WAIT_V(n) asm volatile("s_waitcnt vmcnt(" #n ")" ::: "memory")
; #define PG8_WAIT_L(n) asm volatile("s_waitcnt lgkmcnt(" #n ")" ::: "memory")
; #define PG8_BAR __builtin_amdgcn_s_barrier()
; #define PG8_SCHED __builtin_amdgcn_sched_barrier(0)
; DI void gemm_phase(LAS unsigned char* lds, const Gemm g, const StaticOrder& S, const bool eperm) {
;     ...
;         for (int t = 0; t < nt; t += 2) {
;             const bool last = (t == nt - 2);
;             const char* a1 = cA + (size_t)(t + 1) * kstep;
;             const char* a2 = last ? nA : cA + (size_t)(t + 2) * kstep; const char* b2 = last ? nB : cB + (size_t)(t + 2) * kstep;
;             const char* a3 = a2 + kstep; const char* b3 = b2 + kstep;
;             PG8_LDB(B0, 0, 0); PG8_LDB(B1, 0, 1); PG8_SCHED; PG8_LDA(At, 0, 0); PG8_STAGE(PG8_SA(1, 1), a1 + hstepA, voffA);
;             PG8_WAIT_V(8); PG8_WAIT_L(0); PG8_BAR; PG8_MMA(0, 0, At, B0); PG8_MMA(0, 1, At, B1); PG8_BAR; PG8_SCHED;
;             PG8_LDA(At, 0, 1); PG8_STAGE(PG8_SB(0, 0), b2, voffB); PG8_STAGE(PG8_SB(0, 1), b2 + hstepB, voffB); PG8_STAGE(PG8_SA(0, 0), a2, voffA);
;             PG8_WAIT_V(8); PG8_WAIT_L(0); PG8_BAR; PG8_MMA(1, 0, At, B0); PG8_MMA(1, 1, At, B1); PG8_BAR; PG8_SCHED;
.LBB0_791:
	s_andn2_b64 vcc, exec, s[20:21]
	s_cbranch_vccnz .Lg_zero794
	s_add_u32 s30, s30, 0x100
	s_addc_u32 s31, s31, 0
	s_add_u32 s0, s34, 0x80
	s_addc_u32 s1, s35, 0
	s_mov_b32 s6, 0
	s_add_i32 s34, s6, 2
	s_add_u32 s3, s0, 0x80
	s_addc_u32 s7, s1, 0
	s_add_i32 s33, 0, 0x10000
	s_cmp_eq_u32 s97, s6
	s_cselect_b32 s7, s27, s7
	s_cselect_b32 s6, s26, s3
	s_cselect_b32 s45, s29, s31
	s_cselect_b32 s44, s28, s30
	s_add_i32 s3, 0, 0x14000
	v_add_u32_e32 v142, s33, v184
	v_add_u32_e32 v158, s3, v184
	ds_read_b128 v[130:133], v142
	ds_read_b128 v[134:137], v142 offset:1024
	ds_read_b128 v[138:141], v142 offset:2048
	ds_read_b128 v[142:145], v142 offset:3072
	ds_read_b128 v[146:149], v158
	ds_read_b128 v[150:153], v158 offset:1024
	ds_read_b128 v[154:157], v158 offset:2048
	ds_read_b128 v[158:161], v158 offset:3072
	v_lshl_add_u64 v[180:181], s[0:1], 0, v[174:175]
	s_add_i32 m0, s70, 0xc000
	ds_read_b128 v[162:165], v188
	ds_read_b128 v[176:179], v188 offset:1024
	ds_read_b128 v[194:197], v188 offset:2048
	ds_read_b128 v[200:203], v188 offset:3072
	ds_read_b128 v[204:207], v188 offset:4096
	ds_read_b128 v[236:239], v188 offset:5120
	ds_read_b128 v[240:243], v188 offset:6144
	ds_read_b128 v[244:247], v188 offset:7168
	global_load_lds_dwordx4 v[180:181], off
	v_lshl_add_u64 v[180:181], s[0:1], 0, v[172:173]
	s_add_i32 m0, s70, 0xe000
	s_nop 0
	global_load_lds_dwordx4 v[180:181], off
	s_waitcnt vmcnt(8)
	s_waitcnt lgkmcnt(0)
	s_barrier
	s_setprio 1
	s_waitcnt lgkmcnt(0)
	v_mfma_f32_16x16x32_bf16 v[122:125], v[130:133], v[162:165], 0
	v_mfma_f32_16x16x32_bf16 v[126:129], v[138:141], v[162:165], 0
	v_mfma_f32_16x16x32_bf16 v[110:113], v[130:133], v[194:197], 0
	v_mfma_f32_16x16x32_bf16 v[106:109], v[138:141], v[194:197], 0
	v_mfma_f32_16x16x32_bf16 v[94:97], v[130:133], v[204:207], 0
	v_mfma_f32_16x16x32_bf16 v[90:93], v[138:141], v[204:207], 0
	v_mfma_f32_16x16x32_bf16 v[78:81], v[130:133], v[240:243], 0
	v_mfma_f32_16x16x32_bf16 v[74:77], v[138:141], v[240:243], 0
	v_mfma_f32_16x16x32_bf16 v[122:125], v[134:137], v[176:179], v[122:125]
	v_mfma_f32_16x16x32_bf16 v[126:129], v[142:145], v[176:179], v[126:129]
	v_mfma_f32_16x16x32_bf16 v[110:113], v[134:137], v[200:203], v[110:113]
	v_mfma_f32_16x16x32_bf16 v[106:109], v[142:145], v[200:203], v[106:109]
	v_mfma_f32_16x16x32_bf16 v[94:97], v[134:137], v[236:239], v[94:97]
	v_mfma_f32_16x16x32_bf16 v[90:93], v[142:145], v[236:239], v[90:93]
	v_mfma_f32_16x16x32_bf16 v[78:81], v[134:137], v[244:247], v[78:81]
	v_mfma_f32_16x16x32_bf16 v[74:77], v[142:145], v[244:247], v[74:77]
	s_setprio 0
	s_setprio 1
	v_mfma_f32_16x16x32_bf16 v[118:121], v[146:149], v[162:165], 0
	v_mfma_f32_16x16x32_bf16 v[114:117], v[154:157], v[162:165], 0
	v_mfma_f32_16x16x32_bf16 v[102:105], v[146:149], v[194:197], 0
	v_mfma_f32_16x16x32_bf16 v[98:101], v[154:157], v[194:197], 0
	v_mfma_f32_16x16x32_bf16 v[86:89], v[146:149], v[204:207], 0
	v_mfma_f32_16x16x32_bf16 v[82:85], v[154:157], v[204:207], 0
	v_mfma_f32_16x16x32_bf16 v[70:73], v[146:149], v[240:243], 0
	v_mfma_f32_16x16x32_bf16 v[66:69], v[154:157], v[240:243], 0
	v_mfma_f32_16x16x32_bf16 v[118:121], v[150:153], v[176:179], v[118:121]
	v_mfma_f32_16x16x32_bf16 v[114:117], v[158:161], v[176:179], v[114:117]
	v_mfma_f32_16x16x32_bf16 v[102:105], v[150:153], v[200:203], v[102:105]
	v_mfma_f32_16x16x32_bf16 v[98:101], v[158:161], v[200:203], v[98:101]
	v_mfma_f32_16x16x32_bf16 v[86:89], v[150:153], v[236:239], v[86:89]
	v_mfma_f32_16x16x32_bf16 v[82:85], v[158:161], v[236:239], v[82:85]
	v_mfma_f32_16x16x32_bf16 v[70:73], v[150:153], v[244:247], v[70:73]
	v_mfma_f32_16x16x32_bf16 v[66:69], v[158:161], v[244:247], v[66:69]
	s_setprio 0
	s_barrier
	s_add_i32 s33, s33, s95
	v_lshl_add_u64 v[180:181], s[44:45], 0, v[0:1]
	s_mov_b32 m0, s33
	ds_read_b128 v[162:165], v188 offset:16384
	ds_read_b128 v[176:179], v188 offset:17408
	ds_read_b128 v[194:197], v188 offset:18432
	ds_read_b128 v[200:203], v188 offset:19456
	ds_read_b128 v[204:207], v188 offset:20480
	ds_read_b128 v[236:239], v188 offset:21504
	ds_read_b128 v[240:243], v188 offset:22528
	ds_read_b128 v[244:247], v188 offset:23552
	global_load_lds_dwordx4 v[180:181], off
	s_add_i32 m0, s33, 0x2000
	v_lshl_add_u64 v[190:191], s[44:45], 0, v[168:169]
	s_add_u32 s44, s44, s14
	s_addc_u32 s45, s45, s15
	s_add_i32 s3, s3, s95
	global_load_lds_dwordx4 v[190:191], off
	v_lshl_add_u64 v[208:209], s[44:45], 0, v[0:1]
	s_mov_b32 m0, s3
	v_lshl_add_u64 v[248:249], s[44:45], 0, v[168:169]
	global_load_lds_dwordx4 v[208:209], off
	s_add_i32 m0, s3, 0x2000
	v_lshl_add_u64 v[250:251], s[6:7], 0, v[170:171]
	global_load_lds_dwordx4 v[248:249], off
	s_mov_b32 m0, s70
	v_lshl_add_u64 v[230:231], s[6:7], 0, v[166:167]
	global_load_lds_dwordx4 v[250:251], off
	s_mov_b32 m0, s71
	s_nop 0
	global_load_lds_dwordx4 v[230:231], off
	s_waitcnt vmcnt(8)
	s_waitcnt lgkmcnt(0)
	s_barrier
; #define PG8_STAGE(bufoff, gbase, voff) do { _Pragma("unroll") for (int _i = 0; _i < 2; ++_i) \
;         __builtin_amdgcn_global_load_lds((const unsigned*)((const char*)(gbase) + (voff)[_i]), (LAS unsigned*)(lds + (bufoff) + ldsw + _i * 8192), 16, 0, 0); } while (0)
; #define PG8_LDA(dst, b, h) do { _Pragma("unroll") for (int m = 0; m < 4; ++m) _Pragma("unroll") for (int k = 0; k < 2; ++k) dst[m][k] = *(const LAS bf16x8*)(lds + PG8_SA(b, h) + aoff + m * 2048 + k * 1024); } while (0)
; #define PG8_LDB(dst, b, h) do { _Pragma("unroll") for (int n = 0; n < 2; ++n) _Pragma("unroll") for (int k = 0; k < 2; ++k) dst[n][k] = *(const LAS bf16x8*)(lds + PG8_SB(b, h) + boff + n * 2048 + k * 1024); } while (0)
; #define PG8_MMA(ai, bj, At, Bt) do { __builtin_amdgcn_s_setprio(1); _Pragma("unroll") for (int m = 0; m < 4; ++m) _Pragma("unroll") for (int n = 0; n < 2; ++n) _Pragma("unroll") for (int k = 0; k < 2; ++k) \
;         acc[ai][bj][m][n] = __builtin_amdgcn_mfma_f32_16x16x32_bf16(Bt[n][k], At[m][k], acc[ai][bj][m][n], 0, 0, 0); __builtin_amdgcn_s_setprio(0); } while (0)
; #define PG8_WAIT_V(n) asm volatile("s_waitcnt vmcnt(" #n ")" ::: "memory")
; #define PG8_WAIT_L(n) asm volatile("s_waitcnt lgkmcnt(" #n ")" ::: "memory")
; #define PG8_BAR __builtin_amdgcn_s_barrier()
; #define PG8_SCHED __builtin_amdgcn_sched_barrier(0)
; DI void gemm_phase(LAS unsigned char* lds, const Gemm g, const StaticOrder& S, const bool eperm) {
;     ...
;             PG8_WAIT_V(8); PG8_WAIT_L(0); PG8_BAR; PG8_MMA(1, 0, At, B0); PG8_MMA(1, 1, At, B1); PG8_BAR; PG8_SCHED;
;             PG8_LDB(B0, 1, 0); PG8_LDB(B1, 1, 1); PG8_SCHED; PG8_LDA(At, 1, 0); PG8_STAGE(PG8_SA(0, 1), a2 + hstepA, voffA);
;             PG8_WAIT_V(8); PG8_WAIT_L(0); PG8_BAR; PG8_MMA(0, 0, At, B0); PG8_MMA(0, 1, At, B1); PG8_BAR; PG8_SCHED;
	s_setprio 1
	s_waitcnt lgkmcnt(0)
	v_mfma_f32_16x16x32_bf16 v[62:65], v[130:133], v[162:165], 0
	v_mfma_f32_16x16x32_bf16 v[58:61], v[138:141], v[162:165], 0
	v_mfma_f32_16x16x32_bf16 v[46:49], v[130:133], v[194:197], 0
	v_mfma_f32_16x16x32_bf16 v[42:45], v[138:141], v[194:197], 0
	v_mfma_f32_16x16x32_bf16 v[30:33], v[130:133], v[204:207], 0
	v_mfma_f32_16x16x32_bf16 v[26:29], v[138:141], v[204:207], 0
	v_mfma_f32_16x16x32_bf16 v[14:17], v[130:133], v[240:243], 0
	v_mfma_f32_16x16x32_bf16 v[10:13], v[138:141], v[240:243], 0
	v_mfma_f32_16x16x32_bf16 v[62:65], v[134:137], v[176:179], v[62:65]
	v_mfma_f32_16x16x32_bf16 v[58:61], v[142:145], v[176:179], v[58:61]
	v_mfma_f32_16x16x32_bf16 v[46:49], v[134:137], v[200:203], v[46:49]
	v_mfma_f32_16x16x32_bf16 v[42:45], v[142:145], v[200:203], v[42:45]
	v_mfma_f32_16x16x32_bf16 v[30:33], v[134:137], v[236:239], v[30:33]
	v_mfma_f32_16x16x32_bf16 v[26:29], v[142:145], v[236:239], v[26:29]
	v_mfma_f32_16x16x32_bf16 v[14:17], v[134:137], v[244:247], v[14:17]
	v_mfma_f32_16x16x32_bf16 v[10:13], v[142:145], v[244:247], v[10:13]
	s_setprio 0
	s_setprio 1
	v_mfma_f32_16x16x32_bf16 v[54:57], v[146:149], v[162:165], 0
	v_mfma_f32_16x16x32_bf16 v[50:53], v[154:157], v[162:165], 0
	v_mfma_f32_16x16x32_bf16 v[38:41], v[146:149], v[194:197], 0
	v_mfma_f32_16x16x32_bf16 v[34:37], v[154:157], v[194:197], 0
	v_mfma_f32_16x16x32_bf16 v[22:25], v[146:149], v[204:207], 0
	v_mfma_f32_16x16x32_bf16 v[18:21], v[154:157], v[204:207], 0
	v_mfma_f32_16x16x32_bf16 v[6:9], v[146:149], v[240:243], 0
	v_mfma_f32_16x16x32_bf16 v[2:5], v[154:157], v[240:243], 0
	v_mfma_f32_16x16x32_bf16 v[54:57], v[150:153], v[176:179], v[54:57]
	v_mfma_f32_16x16x32_bf16 v[50:53], v[158:161], v[176:179], v[50:53]
	v_mfma_f32_16x16x32_bf16 v[38:41], v[150:153], v[200:203], v[38:41]
	v_mfma_f32_16x16x32_bf16 v[34:37], v[158:161], v[200:203], v[34:37]
	v_mfma_f32_16x16x32_bf16 v[22:25], v[150:153], v[236:239], v[22:25]
	v_mfma_f32_16x16x32_bf16 v[18:21], v[158:161], v[236:239], v[18:21]
	v_mfma_f32_16x16x32_bf16 v[6:9], v[150:153], v[244:247], v[6:9]
	v_mfma_f32_16x16x32_bf16 v[2:5], v[158:161], v[244:247], v[2:5]
	s_setprio 0
	s_barrier
	s_add_i32 s3, 0, 0x18000
	s_add_i32 s33, 0, 0x1c000
	v_add_u32_e32 v142, s3, v184
	v_add_u32_e32 v158, s33, v184
	ds_read_b128 v[130:133], v142
	ds_read_b128 v[134:137], v142 offset:1024
	ds_read_b128 v[138:141], v142 offset:2048
	ds_read_b128 v[142:145], v142 offset:3072
	ds_read_b128 v[146:149], v158
	ds_read_b128 v[150:153], v158 offset:1024
	ds_read_b128 v[154:157], v158 offset:2048
	ds_read_b128 v[158:161], v158 offset:3072
	s_add_u32 s6, s6, s10
	s_addc_u32 s7, s7, s11
	s_mov_b32 m0, s47
	v_lshl_add_u64 v[232:233], s[6:7], 0, v[170:171]
	ds_read_b128 v[162:165], v188 offset:32768
	ds_read_b128 v[176:179], v188 offset:33792
	ds_read_b128 v[194:197], v188 offset:34816
	ds_read_b128 v[200:203], v188 offset:35840
	ds_read_b128 v[204:207], v188 offset:36864
	ds_read_b128 v[236:239], v188 offset:37888
	ds_read_b128 v[240:243], v188 offset:38912
	ds_read_b128 v[244:247], v188 offset:39936
	global_load_lds_dwordx4 v[232:233], off
	v_lshl_add_u64 v[232:233], s[6:7], 0, v[166:167]
	s_mov_b32 m0, s38
	s_nop 0
	global_load_lds_dwordx4 v[232:233], off
	s_waitcnt vmcnt(8)
	s_waitcnt lgkmcnt(0)
	s_barrier
	s_setprio 1
	s_waitcnt lgkmcnt(0)
	v_mfma_f32_16x16x32_bf16 v[122:125], v[130:133], v[162:165], v[122:125]
	v_mfma_f32_16x16x32_bf16 v[126:129], v[138:141], v[162:165], v[126:129]
	v_mfma_f32_16x16x32_bf16 v[110:113], v[130:133], v[194:197], v[110:113]
	v_mfma_f32_16x16x32_bf16 v[106:109], v[138:141], v[194:197], v[106:109]
	v_mfma_f32_16x16x32_bf16 v[94:97], v[130:133], v[204:207], v[94:97]
	v_mfma_f32_16x16x32_bf16 v[90:93], v[138:141], v[204:207], v[90:93]
	v_mfma_f32_16x16x32_bf16 v[78:81], v[130:133], v[240:243], v[78:81]
	v_mfma_f32_16x16x32_bf16 v[74:77], v[138:141], v[240:243], v[74:77]
	v_mfma_f32_16x16x32_bf16 v[122:125], v[134:137], v[176:179], v[122:125]
	v_mfma_f32_16x16x32_bf16 v[126:129], v[142:145], v[176:179], v[126:129]
	v_mfma_f32_16x16x32_bf16 v[110:113], v[134:137], v[200:203], v[110:113]
	v_mfma_f32_16x16x32_bf16 v[106:109], v[142:145], v[200:203], v[106:109]
	v_mfma_f32_16x16x32_bf16 v[94:97], v[134:137], v[236:239], v[94:97]
	v_mfma_f32_16x16x32_bf16 v[90:93], v[142:145], v[236:239], v[90:93]
	v_mfma_f32_16x16x32_bf16 v[78:81], v[134:137], v[244:247], v[78:81]
	v_mfma_f32_16x16x32_bf16 v[74:77], v[142:145], v[244:247], v[74:77]
	s_setprio 0
	s_setprio 1
	v_mfma_f32_16x16x32_bf16 v[118:121], v[146:149], v[162:165], v[118:121]
	v_mfma_f32_16x16x32_bf16 v[114:117], v[154:157], v[162:165], v[114:117]
	v_mfma_f32_16x16x32_bf16 v[102:105], v[146:149], v[194:197], v[102:105]
	v_mfma_f32_16x16x32_bf16 v[98:101], v[154:157], v[194:197], v[98:101]
	v_mfma_f32_16x16x32_bf16 v[86:89], v[146:149], v[204:207], v[86:89]
	v_mfma_f32_16x16x32_bf16 v[82:85], v[154:157], v[204:207], v[82:85]
	v_mfma_f32_16x16x32_bf16 v[70:73], v[146:149], v[240:243], v[70:73]
	v_mfma_f32_16x16x32_bf16 v[66:69], v[154:157], v[240:243], v[66:69]
	v_mfma_f32_16x16x32_bf16 v[118:121], v[150:153], v[176:179], v[118:121]
	v_mfma_f32_16x16x32_bf16 v[114:117], v[158:161], v[176:179], v[114:117]
	v_mfma_f32_16x16x32_bf16 v[102:105], v[150:153], v[200:203], v[102:105]
	v_mfma_f32_16x16x32_bf16 v[98:101], v[158:161], v[200:203], v[98:101]
	v_mfma_f32_16x16x32_bf16 v[86:89], v[150:153], v[236:239], v[86:89]
	v_mfma_f32_16x16x32_bf16 v[82:85], v[158:161], v[236:239], v[82:85]
	v_mfma_f32_16x16x32_bf16 v[70:73], v[150:153], v[244:247], v[70:73]
	v_mfma_f32_16x16x32_bf16 v[66:69], v[158:161], v[244:247], v[66:69]
	s_setprio 0
	s_barrier
; #define PG8_STAGE(bufoff, gbase, voff) do { _Pragma("unroll") for (int _i = 0; _i < 2; ++_i) \
;         __builtin_amdgcn_global_load_lds((const unsigned*)((const char*)(gbase) + (voff)[_i]), (LAS unsigned*)(lds + (bufoff) + ldsw + _i * 8192), 16, 0, 0); } while (0)
; #define PG8_LDA(dst, b, h) do { _Pragma("unroll") for (int m = 0; m < 4; ++m) _Pragma("unroll") for (int k = 0; k < 2; ++k) dst[m][k] = *(const LAS bf16x8*)(lds + PG8_SA(b, h) + aoff + m * 2048 + k * 1024); } while (0)
; #define PG8_MMA(ai, bj, At, Bt) do { __builtin_amdgcn_s_setprio(1); _Pragma("unroll") for (int m = 0; m < 4; ++m) _Pragma("unroll") for (int n = 0; n < 2; ++n) _Pragma("unroll") for (int k = 0; k < 2; ++k) \
;         acc[ai][bj][m][n] = __builtin_amdgcn_mfma_f32_16x16x32_bf16(Bt[n][k], At[m][k], acc[ai][bj][m][n], 0, 0, 0); __builtin_amdgcn_s_setprio(0); } while (0)
; #define PG8_WAIT_V(n) asm volatile("s_waitcnt vmcnt(" #n ")" ::: "memory")
; #define PG8_WAIT_L(n) asm volatile("s_waitcnt lgkmcnt(" #n ")" ::: "memory")
; #define PG8_BAR __builtin_amdgcn_s_barrier()
; #define PG8_SCHED __builtin_amdgcn_sched_barrier(0)
; DI void gemm_phase(LAS unsigned char* lds, const Gemm g, const StaticOrder& S, const bool eperm) {
;     ...
;             PG8_LDA(At, 1, 1); PG8_STAGE(PG8_SB(1, 0), b3, voffB); PG8_STAGE(PG8_SB(1, 1), b3 + hstepB, voffB); PG8_STAGE(PG8_SA(1, 0), a3, voffA);
;             PG8_WAIT_V(8); PG8_WAIT_L(0); PG8_BAR; PG8_MMA(1, 0, At, B0); PG8_MMA(1, 1, At, B1); PG8_BAR; PG8_SCHED;
;         }
	s_add_i32 s3, s3, s95
	v_lshl_add_u64 v[180:181], v[180:181], 0, s[86:87]
	s_mov_b32 m0, s3
	ds_read_b128 v[162:165], v188 offset:49152
	ds_read_b128 v[176:179], v188 offset:50176
	ds_read_b128 v[194:197], v188 offset:51200
	ds_read_b128 v[200:203], v188 offset:52224
	ds_read_b128 v[204:207], v188 offset:53248
	ds_read_b128 v[236:239], v188 offset:54272
	ds_read_b128 v[240:243], v188 offset:55296
	ds_read_b128 v[244:247], v188 offset:56320
	global_load_lds_dwordx4 v[180:181], off
	v_lshl_add_u64 v[180:181], v[190:191], 0, s[86:87]
	s_add_i32 m0, s3, 0x2000
	s_add_i32 s3, s33, s95
	global_load_lds_dwordx4 v[180:181], off
	v_lshl_add_u64 v[180:181], v[208:209], 0, s[86:87]
	s_mov_b32 m0, s3
	s_nop 0
	global_load_lds_dwordx4 v[180:181], off
	v_lshl_add_u64 v[180:181], v[248:249], 0, s[86:87]
	s_add_i32 m0, s3, 0x2000
	s_nop 0
	global_load_lds_dwordx4 v[180:181], off
	v_lshl_add_u64 v[180:181], v[250:251], 0, s[86:87]
	s_mov_b32 m0, s79
	s_nop 0
	global_load_lds_dwordx4 v[180:181], off
	v_lshl_add_u64 v[180:181], v[230:231], 0, s[86:87]
	s_mov_b32 m0, s96
	s_nop 0
	global_load_lds_dwordx4 v[180:181], off
	s_waitcnt vmcnt(8)
	s_waitcnt lgkmcnt(0)
	s_barrier
	s_setprio 1
	s_waitcnt lgkmcnt(0)
	v_mfma_f32_16x16x32_bf16 v[62:65], v[130:133], v[162:165], v[62:65]
	v_mfma_f32_16x16x32_bf16 v[58:61], v[138:141], v[162:165], v[58:61]
	v_mfma_f32_16x16x32_bf16 v[46:49], v[130:133], v[194:197], v[46:49]
	v_mfma_f32_16x16x32_bf16 v[42:45], v[138:141], v[194:197], v[42:45]
	v_mfma_f32_16x16x32_bf16 v[30:33], v[130:133], v[204:207], v[30:33]
	v_mfma_f32_16x16x32_bf16 v[26:29], v[138:141], v[204:207], v[26:29]
	v_mfma_f32_16x16x32_bf16 v[14:17], v[130:133], v[240:243], v[14:17]
	v_mfma_f32_16x16x32_bf16 v[10:13], v[138:141], v[240:243], v[10:13]
	v_mfma_f32_16x16x32_bf16 v[62:65], v[134:137], v[176:179], v[62:65]
	v_mfma_f32_16x16x32_bf16 v[58:61], v[142:145], v[176:179], v[58:61]
	v_mfma_f32_16x16x32_bf16 v[46:49], v[134:137], v[200:203], v[46:49]
	v_mfma_f32_16x16x32_bf16 v[42:45], v[142:145], v[200:203], v[42:45]
	v_mfma_f32_16x16x32_bf16 v[30:33], v[134:137], v[236:239], v[30:33]
	v_mfma_f32_16x16x32_bf16 v[26:29], v[142:145], v[236:239], v[26:29]
	v_mfma_f32_16x16x32_bf16 v[14:17], v[134:137], v[244:247], v[14:17]
	v_mfma_f32_16x16x32_bf16 v[10:13], v[142:145], v[244:247], v[10:13]
	s_setprio 0
	s_setprio 1
	v_mfma_f32_16x16x32_bf16 v[54:57], v[146:149], v[162:165], v[54:57]
	v_mfma_f32_16x16x32_bf16 v[50:53], v[154:157], v[162:165], v[50:53]
	v_mfma_f32_16x16x32_bf16 v[38:41], v[146:149], v[194:197], v[38:41]
	v_mfma_f32_16x16x32_bf16 v[34:37], v[154:157], v[194:197], v[34:37]
	v_mfma_f32_16x16x32_bf16 v[22:25], v[146:149], v[204:207], v[22:25]
	v_mfma_f32_16x16x32_bf16 v[18:21], v[154:157], v[204:207], v[18:21]
	v_mfma_f32_16x16x32_bf16 v[6:9], v[146:149], v[240:243], v[6:9]
	v_mfma_f32_16x16x32_bf16 v[2:5], v[154:157], v[240:243], v[2:5]
	v_mfma_f32_16x16x32_bf16 v[54:57], v[150:153], v[176:179], v[54:57]
	v_mfma_f32_16x16x32_bf16 v[50:53], v[158:161], v[176:179], v[50:53]
	v_mfma_f32_16x16x32_bf16 v[38:41], v[150:153], v[200:203], v[38:41]
	v_mfma_f32_16x16x32_bf16 v[34:37], v[158:161], v[200:203], v[34:37]
	v_mfma_f32_16x16x32_bf16 v[22:25], v[150:153], v[236:239], v[22:25]
	v_mfma_f32_16x16x32_bf16 v[18:21], v[158:161], v[236:239], v[18:21]
	v_mfma_f32_16x16x32_bf16 v[6:9], v[150:153], v[244:247], v[6:9]
	v_mfma_f32_16x16x32_bf16 v[2:5], v[158:161], v[244:247], v[2:5]
	s_setprio 0
	s_barrier
	s_add_u32 s30, s30, 0x100
	s_addc_u32 s31, s31, 0
	s_add_u32 s0, s0, 0x100
	s_addc_u32 s1, s1, 0
	s_cmp_ge_i32 s34, s39
	s_mov_b32 s6, s34
	s_cbranch_scc0 .LBB0_793
	s_branch .LBB0_794
